# ctx units on RG workgroups + dt pass always spread to the workgroups without a last-round tile
# baseline (speedup 1.0000x reference)
.LBB0_330:
	s_xor_b64 s[0:1], s[82:83], -1
	v_writelane_b32 v254, s0, 59
	s_mov_b64 s[22:23], s[88:89]
	s_mul_i32 s14, s16, 0x120000
	v_writelane_b32 v254, s1, 60
	s_and_b64 s[0:1], s[82:83], exec
	s_movk_i32 s0, 0x90
	s_cselect_b32 s13, s0, 0x80
	v_readlane_b32 s0, v254, 2
	v_readlane_b32 s1, v254, 3
	s_cselect_b32 s20, 0, 0x70
	v_writelane_b32 v254, s2, 61
	s_and_b64 s[0:1], s[0:1], s[2:3]
	s_and_b64 s[0:1], s[0:1], exec
	s_mul_i32 s21, s13, 11
	v_writelane_b32 v254, s3, 62
	s_cselect_b32 s0, 0xfffffdc0, 0
	s_cselect_b32 s51, 0x240, 0
	s_add_i32 s2, s21, s20
	s_add_i32 s0, s2, s0
	s_lshl_b32 s62, s16, 13
	s_lshl_b32 s36, s16, 3
	s_add_i32 s51, s51, s73
	s_cmp_lt_i32 s51, 2.0
	s_cselect_b64 s[4:5], -1, 0
	s_cmp_ge_i32 s51, s21
	s_cselect_b64 s[2:3], -1, 0
	v_writelane_b32 v254, s2, 63
	s_mov_b32 s15, s37
	s_mul_i32 s12, s16, 0x1800000
	v_writelane_b32 v255, s3, 0
	s_sub_i32 s2, s51, s21
	s_cmp_lt_i32 s2, s20
	s_cselect_b64 s[6:7], -1, 0
	s_ashr_i32 s3, s2, 4
	v_writelane_b32 v255, s6, 1
	s_cmp_gt_i32 s3, 2
	s_mul_i32 s1, s16, 0x2ec00
	v_writelane_b32 v255, s7, 2
	s_cselect_b32 s6, 4, 2
	s_add_i32 s6, s6, s3
	s_cmp_gt_u32 s2, 15
	s_cselect_b32 s2, s6, 0
	v_writelane_b32 v255, s2, 3
	s_ashr_i32 s2, s51, 31
	s_lshr_b32 s2, s2, 29
	s_add_i32 s2, s51, s2
	s_ashr_i32 s9, s2, 3
	s_and_b32 s6, s2, -8
	s_load_dwordx2 s[2:3], s[22:23], 0xf0
	s_lshr_b32 s18, s21, 3
	s_sub_i32 s10, s51, s6
	s_mov_b32 s6, s14
	v_writelane_b32 v255, s6, 4
	s_waitcnt lgkmcnt(0)
	s_add_u32 s19, s2, 0x5400000
	s_addc_u32 s42, s3, 0
	s_lshl_b64 s[14:15], s[14:15], 2
	v_writelane_b32 v255, s7, 5
	s_add_u32 s6, s2, s14
	v_writelane_b32 v255, s14, 6
	s_addc_u32 s7, s3, s15
	s_add_u32 s24, s6, 0x800000
	s_addc_u32 s25, s7, 0
	s_add_u32 s6, s2, s12
	s_addc_u32 s7, s3, 0
	s_add_u32 s43, s6, 0x1400000
	s_addc_u32 s46, s7, 0
	s_add_u32 s26, s2, 0x9c00000
	s_addc_u32 s27, s3, 0
	s_add_u32 s1, s2, s1
	s_addc_u32 s6, s3, 0
	s_add_u32 s47, s1, 0x200000
	s_addc_u32 s90, s6, 0
	s_add_u32 s28, s2, 0x400000
	s_addc_u32 s29, s3, 0
	s_ashr_i32 s1, s0, 31
	s_abs_i32 s0, s0
	v_readlane_b32 s6, v254, 29
	s_mul_hi_u32 s6, s0, s6
	v_readlane_b32 s7, v254, 30
	s_mul_i32 s6, s6, s7
	s_sub_i32 s0, s0, s6
	s_sub_i32 s6, s0, s7
	s_cmp_ge_u32 s0, s7
	s_cselect_b32 s0, s6, s0
	s_sub_i32 s6, s0, s7
	s_cmp_ge_u32 s0, s7
	s_cselect_b32 s0, s6, s0
	v_writelane_b32 v255, s15, 7
	s_xor_b32 s0, s0, s1
	v_writelane_b32 v255, s12, 8
	s_sub_i32 s12, s0, s1
	s_cmp_lg_u32 s12, 0
	s_cselect_b64 s[0:1], -1, 0
	s_mov_b32 s6, s12
	s_cmp_le_i32 s6, s85
	s_cselect_b64 s[6:7], -1, 0
	s_and_b64 s[30:31], s[0:1], s[6:7]
	s_cmp_lt_i32 s73, s12
	s_cselect_b64 s[38:39], -1, 0
	s_add_u32 s40, s2, 0x410000
	s_addc_u32 s41, s3, 0
	s_add_u32 s0, s2, 0x500000
	s_addc_u32 s1, s3, 0
	v_writelane_b32 v255, s0, 9
	s_sub_i32 s6, s73, s12
	s_mov_b32 s11, s96
	v_writelane_b32 v255, s1, 10
	s_and_b64 s[0:1], s[30:31], exec
	s_cselect_b32 s0, s6, s91
	s_lshl_b32 s91, s0, 3
	s_sub_i32 s0, s85, s12
	v_mbcnt_lo_u32_b32 v206, -1, 0
	v_mbcnt_hi_u32_b32 v206, -1, v206
	s_add_i32 s91, s91, s11
	s_lshl_b32 s6, s0, 3
	s_and_b64 s[0:1], s[30:31], exec
	v_readlane_b32 s0, v254, 49
	s_cselect_b32 s93, s6, s0
	s_cmp_lt_i32 s91, 0x9000
	s_cselect_b64 s[60:61], -1, 0
	s_sub_i32 s0, s93, s91
	s_mul_i32 s8, s16, 0x220
	v_readlane_b32 s1, v254, 50
	s_add_i32 s0, s0, 0x8fff
	s_add_u32 s1, s2, s8
	s_addc_u32 s6, s3, 0
	s_mov_b32 s14, s16
	s_add_u32 s16, s1, 0x280000
	s_addc_u32 s17, s6, 0
	v_readlane_b32 s6, v254, 40
	v_writelane_b32 v255, s16, 11
	v_readlane_b32 s7, v254, 41
	s_lshr_b32 s1, s10, 31
	v_writelane_b32 v255, s17, 12
	s_and_b64 s[16:17], s[6:7], s[4:5]
	s_abs_i32 s4, s93
	v_cvt_f32_u32_e32 v0, s4
	s_or_b32 s1, s18, s1
	s_mul_i32 s1, s1, s10
	s_add_i32 s1, s1, s9
	v_rcp_iflag_f32_e32 v0, v0
	s_mul_hi_i32 s5, s1, 0x2e8ba2e9
	s_lshr_b32 s6, s5, 31
	s_ashr_i32 s5, s5, 4
	v_mul_f32_e32 v0, 0x4f7ffffe, v0
	v_cvt_u32_f32_e32 v0, v0
	s_sub_i32 s7, 0, s4
	s_add_i32 s5, s5, s6
	s_lshl_b32 s6, s5, 3
	v_readfirstlane_b32 s8, v0
	s_mul_i32 s7, s7, s8
	s_mulk_i32 s5, 0x58
	s_mul_hi_u32 s7, s8, s7
	s_sub_i32 s1, s1, s5
	s_abs_i32 s5, s0
	s_add_i32 s8, s8, s7
	s_mul_hi_u32 s7, s5, s8
	s_mul_i32 s8, s7, s4
	s_sub_i32 s5, s5, s8
	s_sub_i32 s8, s13, s6
	s_xor_b32 s0, s0, s93
	s_min_i32 s8, s8, 8
	s_ashr_i32 s0, s0, 31
	s_add_i32 s9, s7, 1
	s_sub_i32 s10, s5, s4
	s_cmp_ge_u32 s5, s4
	s_cselect_b32 s7, s9, s7
	s_cselect_b32 s5, s10, s5
	s_add_i32 s9, s7, 1
	s_cmp_ge_u32 s5, s4
	s_cselect_b32 s4, s9, s7
	s_abs_i32 s5, s8
	v_cvt_f32_u32_e32 v0, s5
	s_xor_b32 s4, s4, s0
	v_writelane_b32 v255, s13, 13
	s_sub_i32 s0, s4, s0
	v_rcp_iflag_f32_e32 v0, v0
	v_writelane_b32 v255, s0, 14
	s_sub_i32 s0, 0, s5
	s_mov_b32 s15, s37
	v_mul_f32_e32 v0, 0x4f7ffffe, v0
	v_cvt_u32_f32_e32 v0, v0
	v_lshl_add_u32 v207, s11, 6, v206
	s_mov_b32 s50, s62
	v_readfirstlane_b32 s4, v0
	s_mul_i32 s0, s0, s4
	s_mul_hi_u32 s0, s4, s0
	s_add_i32 s4, s4, s0
	s_abs_i32 s0, s1
	s_mul_hi_u32 s4, s0, s4
	s_mul_i32 s7, s4, s5
	s_sub_i32 s0, s0, s7
	s_xor_b32 s7, s1, s8
	s_ashr_i32 s7, s7, 31
	s_add_i32 s9, s4, 1
	s_sub_i32 s10, s0, s5
	s_cmp_ge_u32 s0, s5
	s_cselect_b32 s4, s9, s4
	s_cselect_b32 s0, s10, s0
	s_add_i32 s9, s4, 1
	s_cmp_ge_u32 s0, s5
	s_cselect_b32 s0, s9, s4
	s_xor_b32 s0, s0, s7
	s_sub_i32 s0, s0, s7
	s_mov_b32 s89, s0
	s_mul_i32 s0, s0, s8
	s_sub_i32 s0, s1, s0
	s_add_i32 s0, s6, s0
	v_writelane_b32 v255, s0, 15
	v_writelane_b32 v255, s14, 16
	s_lshl_b64 s[0:1], s[14:15], 15
	s_add_u32 s0, s40, s0
	v_writelane_b32 v255, s15, 17
	s_addc_u32 s1, s41, s1
	v_writelane_b32 v255, s0, 18
	s_mov_b64 s[6:7], -1
	s_nop 0
	v_writelane_b32 v255, s1, 19
	s_add_u32 s0, s2, 0x5400070
	s_addc_u32 s1, s3, 0
	v_writelane_b32 v255, s0, 20
	s_nop 1
	v_writelane_b32 v255, s1, 21
	v_writelane_b32 v255, s16, 22
	s_nop 1
	v_writelane_b32 v255, s17, 23
	s_branch .LBB0_334
